# prep: fp8 table-conversion items fetched four at a time (16 loads in flight, counted waits)
# speedup vs baseline: 1.0031x; 1.0031x over previous
; DEVI void convert_chunk_fp8(const float* __restrict__ src, unsigned char* __restrict__ dst, float scale, int tid) {
;   int o = tid * 16;
;   uint4 r;
;   unsigned rr[4];
; #pragma unroll
;   for (int q = 0; q < 4; ++q) {
;     float4 a = *reinterpret_cast<const float4*>(src + o + q * 4);
;     int p = __builtin_amdgcn_cvt_pk_fp8_f32(a.x * scale, a.y * scale, 0, false);
;     p = __builtin_amdgcn_cvt_pk_fp8_f32(a.z * scale, a.w * scale, p, true);
;     rr[q] = (unsigned)p;
;   }
;   r = make_uint4(rr[0], rr[1], rr[2], rr[3]);
;   *reinterpret_cast<uint4*>(dst + o) = r;
; }
; DEVI void phase_prep(const Params& P, int l, char* smem) {
;     ...
;     } else if (id < C2) {
;       int q = id - C1;
;       convert_chunk_fp8(P.in[27] + (long)l * 16777216 + (long)q * 4096, (unsigned char*)(ws + O_VTB) + (long)q * 4096, V_SCALE, tid);
.LBB0_17:
	s_andn2_b64 vcc, exec, s[44:45]
	s_cbranch_vccnz .LBB0_19
	s_add_i32 s24, s51, 0xffffdd40
	s_cmpk_gt_u32 s51, 0x2cbf
	s_cbranch_scc1 .Lpb_v_single
	s_lshl_b64 s[44:45], s[24:25], 14
	v_lshl_add_u64 v[104:105], v[14:15], 0, s[44:45]
	s_mov_b64 s[44:45], 0x800000
	global_load_dwordx4 v[108:111], v[104:105], off
	global_load_dwordx4 v[112:115], v[104:105], off offset:16
	global_load_dwordx4 v[116:119], v[104:105], off offset:32
	global_load_dwordx4 v[120:123], v[104:105], off offset:48
	v_lshl_add_u64 v[104:105], v[104:105], 0, s[44:45]
	global_load_dwordx4 v[144:147], v[104:105], off
	global_load_dwordx4 v[148:151], v[104:105], off offset:16
	global_load_dwordx4 v[152:155], v[104:105], off offset:32
	global_load_dwordx4 v[156:159], v[104:105], off offset:48
	v_lshl_add_u64 v[104:105], v[104:105], 0, s[44:45]
	global_load_dwordx4 v[160:163], v[104:105], off
	global_load_dwordx4 v[164:167], v[104:105], off offset:16
	global_load_dwordx4 v[168:171], v[104:105], off offset:32
	global_load_dwordx4 v[172:175], v[104:105], off offset:48
	v_lshl_add_u64 v[104:105], v[104:105], 0, s[44:45]
	global_load_dwordx4 v[208:211], v[104:105], off
	global_load_dwordx4 v[212:215], v[104:105], off offset:16
	global_load_dwordx4 v[216:219], v[104:105], off offset:32
	global_load_dwordx4 v[220:223], v[104:105], off offset:48
	s_lshl_b64 s[44:45], s[24:25], 12
	v_lshl_add_u64 v[106:107], v[4:5], 0, s[44:45]
	s_mov_b64 s[44:45], 0x200000
	s_waitcnt vmcnt(12)
	v_mov_b32_e32 v224, v89
	v_mov_b32_e32 v225, v89
	v_mov_b32_e32 v226, v89
	v_mov_b32_e32 v227, v89
	v_mul_f32_e32 v108, 0x41000000, v108
	v_mul_f32_e32 v109, 0x41000000, v109
	v_mul_f32_e32 v110, 0x41000000, v110
	v_mul_f32_e32 v111, 0x41000000, v111
	v_mul_f32_e32 v112, 0x41000000, v112
	v_mul_f32_e32 v113, 0x41000000, v113
	v_mul_f32_e32 v114, 0x41000000, v114
	v_mul_f32_e32 v115, 0x41000000, v115
	v_mul_f32_e32 v116, 0x41000000, v116
	v_mul_f32_e32 v117, 0x41000000, v117
	v_mul_f32_e32 v118, 0x41000000, v118
	v_mul_f32_e32 v119, 0x41000000, v119
	v_mul_f32_e32 v120, 0x41000000, v120
	v_mul_f32_e32 v121, 0x41000000, v121
	v_mul_f32_e32 v122, 0x41000000, v122
	v_mul_f32_e32 v123, 0x41000000, v123
	v_cvt_pk_fp8_f32 v224, v108, v109
	v_cvt_pk_fp8_f32 v225, v112, v113
	v_cvt_pk_fp8_f32 v226, v116, v117
	v_cvt_pk_fp8_f32 v227, v120, v121
	v_cvt_pk_fp8_f32 v224, v110, v111 op_sel:[0,0,1]
	v_cvt_pk_fp8_f32 v225, v114, v115 op_sel:[0,0,1]
	v_cvt_pk_fp8_f32 v226, v118, v119 op_sel:[0,0,1]
	v_cvt_pk_fp8_f32 v227, v122, v123 op_sel:[0,0,1]
	global_store_dwordx4 v[106:107], v[224:227], off
	s_nop 0
	v_lshl_add_u64 v[106:107], v[106:107], 0, s[44:45]
	s_waitcnt vmcnt(9)
	v_mov_b32_e32 v228, v89
	v_mov_b32_e32 v229, v89
	v_mov_b32_e32 v230, v89
	v_mov_b32_e32 v231, v89
	v_mul_f32_e32 v144, 0x41000000, v144
	v_mul_f32_e32 v145, 0x41000000, v145
	v_mul_f32_e32 v146, 0x41000000, v146
	v_mul_f32_e32 v147, 0x41000000, v147
	v_mul_f32_e32 v148, 0x41000000, v148
	v_mul_f32_e32 v149, 0x41000000, v149
	v_mul_f32_e32 v150, 0x41000000, v150
	v_mul_f32_e32 v151, 0x41000000, v151
	v_mul_f32_e32 v152, 0x41000000, v152
	v_mul_f32_e32 v153, 0x41000000, v153
	v_mul_f32_e32 v154, 0x41000000, v154
	v_mul_f32_e32 v155, 0x41000000, v155
	v_mul_f32_e32 v156, 0x41000000, v156
	v_mul_f32_e32 v157, 0x41000000, v157
	v_mul_f32_e32 v158, 0x41000000, v158
	v_mul_f32_e32 v159, 0x41000000, v159
	v_cvt_pk_fp8_f32 v228, v144, v145
	v_cvt_pk_fp8_f32 v229, v148, v149
	v_cvt_pk_fp8_f32 v230, v152, v153
	v_cvt_pk_fp8_f32 v231, v156, v157
	v_cvt_pk_fp8_f32 v228, v146, v147 op_sel:[0,0,1]
	v_cvt_pk_fp8_f32 v229, v150, v151 op_sel:[0,0,1]
	v_cvt_pk_fp8_f32 v230, v154, v155 op_sel:[0,0,1]
	v_cvt_pk_fp8_f32 v231, v158, v159 op_sel:[0,0,1]
	global_store_dwordx4 v[106:107], v[228:231], off
	s_nop 0
	v_lshl_add_u64 v[106:107], v[106:107], 0, s[44:45]
	s_waitcnt vmcnt(6)
	v_mov_b32_e32 v232, v89
	v_mov_b32_e32 v233, v89
	v_mov_b32_e32 v234, v89
	v_mov_b32_e32 v235, v89
	v_mul_f32_e32 v160, 0x41000000, v160
	v_mul_f32_e32 v161, 0x41000000, v161
	v_mul_f32_e32 v162, 0x41000000, v162
	v_mul_f32_e32 v163, 0x41000000, v163
	v_mul_f32_e32 v164, 0x41000000, v164
	v_mul_f32_e32 v165, 0x41000000, v165
	v_mul_f32_e32 v166, 0x41000000, v166
	v_mul_f32_e32 v167, 0x41000000, v167
	v_mul_f32_e32 v168, 0x41000000, v168
	v_mul_f32_e32 v169, 0x41000000, v169
	v_mul_f32_e32 v170, 0x41000000, v170
	v_mul_f32_e32 v171, 0x41000000, v171
	v_mul_f32_e32 v172, 0x41000000, v172
	v_mul_f32_e32 v173, 0x41000000, v173
	v_mul_f32_e32 v174, 0x41000000, v174
	v_mul_f32_e32 v175, 0x41000000, v175
	v_cvt_pk_fp8_f32 v232, v160, v161
	v_cvt_pk_fp8_f32 v233, v164, v165
	v_cvt_pk_fp8_f32 v234, v168, v169
	v_cvt_pk_fp8_f32 v235, v172, v173
	v_cvt_pk_fp8_f32 v232, v162, v163 op_sel:[0,0,1]
	v_cvt_pk_fp8_f32 v233, v166, v167 op_sel:[0,0,1]
	v_cvt_pk_fp8_f32 v234, v170, v171 op_sel:[0,0,1]
	v_cvt_pk_fp8_f32 v235, v174, v175 op_sel:[0,0,1]
	global_store_dwordx4 v[106:107], v[232:235], off
	s_nop 0
	v_lshl_add_u64 v[106:107], v[106:107], 0, s[44:45]
	s_waitcnt vmcnt(3)
	v_mov_b32_e32 v236, v89
	v_mov_b32_e32 v237, v89
	v_mov_b32_e32 v238, v89
	v_mov_b32_e32 v239, v89
	v_mul_f32_e32 v208, 0x41000000, v208
	v_mul_f32_e32 v209, 0x41000000, v209
	v_mul_f32_e32 v210, 0x41000000, v210
	v_mul_f32_e32 v211, 0x41000000, v211
	v_mul_f32_e32 v212, 0x41000000, v212
	v_mul_f32_e32 v213, 0x41000000, v213
	v_mul_f32_e32 v214, 0x41000000, v214
	v_mul_f32_e32 v215, 0x41000000, v215
	v_mul_f32_e32 v216, 0x41000000, v216
	v_mul_f32_e32 v217, 0x41000000, v217
	v_mul_f32_e32 v218, 0x41000000, v218
	v_mul_f32_e32 v219, 0x41000000, v219
	v_mul_f32_e32 v220, 0x41000000, v220
	v_mul_f32_e32 v221, 0x41000000, v221
	v_mul_f32_e32 v222, 0x41000000, v222
	v_mul_f32_e32 v223, 0x41000000, v223
	v_cvt_pk_fp8_f32 v236, v208, v209
	v_cvt_pk_fp8_f32 v237, v212, v213
	v_cvt_pk_fp8_f32 v238, v216, v217
	v_cvt_pk_fp8_f32 v239, v220, v221
	v_cvt_pk_fp8_f32 v236, v210, v211 op_sel:[0,0,1]
	v_cvt_pk_fp8_f32 v237, v214, v215 op_sel:[0,0,1]
	v_cvt_pk_fp8_f32 v238, v218, v219 op_sel:[0,0,1]
	v_cvt_pk_fp8_f32 v239, v222, v223 op_sel:[0,0,1]
	global_store_dwordx4 v[106:107], v[236:239], off
	v_readlane_b32 s4, v252, 15
	s_nop 0
	s_mul_i32 s4, s4, 3
	s_add_i32 s50, s50, s4
	v_readlane_b32 s4, v252, 17
	s_nop 0
	s_mul_i32 s4, s4, 3
	s_add_i32 s49, s49, s4
	v_readlane_b32 s4, v252, 19
	s_nop 0
	s_mul_i32 s4, s4, 3
	s_add_i32 s48, s48, s4
	v_readlane_b32 s4, v252, 21
	s_nop 0
	s_mul_i32 s4, s4, 3
	s_add_i32 s47, s47, s4
	v_readlane_b32 s4, v252, 23
	s_nop 0
	s_mul_i32 s4, s4, 3
	s_add_i32 s46, s46, s4
	s_mul_i32 s4, s23, 3
	s_add_i32 s51, s51, s4
	s_mul_i32 s4, s72, 3
	s_add_i32 s1, s1, s4
	s_branch .LBB0_19
; DEVI void convert_chunk_fp8(const float* __restrict__ src, unsigned char* __restrict__ dst, float scale, int tid) {
;   int o = tid * 16;
;   uint4 r;
;   unsigned rr[4];
; #pragma unroll
;   for (int q = 0; q < 4; ++q) {
;     float4 a = *reinterpret_cast<const float4*>(src + o + q * 4);
;     int p = __builtin_amdgcn_cvt_pk_fp8_f32(a.x * scale, a.y * scale, 0, false);
;     p = __builtin_amdgcn_cvt_pk_fp8_f32(a.z * scale, a.w * scale, p, true);
;     rr[q] = (unsigned)p;
;   }
;   r = make_uint4(rr[0], rr[1], rr[2], rr[3]);
;   *reinterpret_cast<uint4*>(dst + o) = r;
; }
.Lpb_v_single:
	s_lshl_b64 s[44:45], s[24:25], 14
	v_lshl_add_u64 v[30:31], v[14:15], 0, s[44:45]
	global_load_dwordx4 v[26:29], v[30:31], off
	global_load_dwordx4 v[50:53], v[30:31], off offset:16
	global_load_dwordx4 v[54:57], v[30:31], off offset:32
	global_load_dwordx4 v[58:61], v[30:31], off offset:48
	v_mov_b32_e32 v100, v89
	v_mov_b32_e32 v101, v89
	v_mov_b32_e32 v102, v89
	v_mov_b32_e32 v103, v89
	s_lshl_b64 s[44:45], s[24:25], 12
	s_waitcnt vmcnt(3)
	v_mul_f32_e32 v25, 0x41000000, v26
	v_mul_f32_e32 v26, 0x41000000, v27
	v_mul_f32_e32 v27, 0x41000000, v28
	v_mul_f32_e32 v28, 0x41000000, v29
	s_waitcnt vmcnt(2)
	v_mul_f32_e32 v29, 0x41000000, v50
	v_mul_f32_e32 v30, 0x41000000, v51
	s_waitcnt vmcnt(1)
	v_mul_f32_e32 v50, 0x41000000, v54
	v_mul_f32_e32 v51, 0x41000000, v55
	s_waitcnt vmcnt(0)
	v_mul_f32_e32 v54, 0x41000000, v58
	v_mul_f32_e32 v55, 0x41000000, v59
	v_cvt_pk_fp8_f32 v100, v25, v26
	v_cvt_pk_fp8_f32 v101, v29, v30
	v_cvt_pk_fp8_f32 v102, v50, v51
	v_cvt_pk_fp8_f32 v103, v54, v55
	v_mul_f32_e32 v31, 0x41000000, v52
	v_mul_f32_e32 v49, 0x41000000, v53
	v_mul_f32_e32 v52, 0x41000000, v56
	v_mul_f32_e32 v53, 0x41000000, v57
	v_mul_f32_e32 v56, 0x41000000, v60
	v_mul_f32_e32 v57, 0x41000000, v61
	v_cvt_pk_fp8_f32 v100, v27, v28 op_sel:[0,0,1]
	v_cvt_pk_fp8_f32 v101, v31, v49 op_sel:[0,0,1]
	v_cvt_pk_fp8_f32 v102, v52, v53 op_sel:[0,0,1]
	v_cvt_pk_fp8_f32 v103, v56, v57 op_sel:[0,0,1]
	v_lshl_add_u64 v[26:27], v[4:5], 0, s[44:45]
	global_store_dwordx4 v[26:27], v[100:103], off

; DEVI void convert_chunk_fp8(const float* __restrict__ src, unsigned char* __restrict__ dst, float scale, int tid) {
;   int o = tid * 16;
;   uint4 r;
;   unsigned rr[4];
; #pragma unroll
;   for (int q = 0; q < 4; ++q) {
;     float4 a = *reinterpret_cast<const float4*>(src + o + q * 4);
;     int p = __builtin_amdgcn_cvt_pk_fp8_f32(a.x * scale, a.y * scale, 0, false);
;     p = __builtin_amdgcn_cvt_pk_fp8_f32(a.z * scale, a.w * scale, p, true);
;     rr[q] = (unsigned)p;
;   }
;   r = make_uint4(rr[0], rr[1], rr[2], rr[3]);
;   *reinterpret_cast<uint4*>(dst + o) = r;
; }
; DEVI void phase_prep(const Params& P, int l, char* smem) {
;     ...
;     } else if (id < C1) {
;       int q = id - C0;
;       convert_chunk_fp8(P.in[26] + (long)l * 16777216 + (long)q * 4096, (unsigned char*)(ws + O_UTB) + (long)q * 4096, U_SCALE, tid);
.LBB0_20:
	s_andn2_b64 vcc, exec, s[44:45]
	s_cbranch_vccnz .LBB0_22
	s_add_i32 s24, s51, 0xffffed40
	s_cmpk_gt_u32 s51, 0x1cbf
	s_cbranch_scc1 .Lpb_u_single
	s_lshl_b64 s[44:45], s[24:25], 14
	v_lshl_add_u64 v[104:105], v[16:17], 0, s[44:45]
	s_mov_b64 s[44:45], 0x800000
	global_load_dwordx4 v[108:111], v[104:105], off
	global_load_dwordx4 v[112:115], v[104:105], off offset:16
	global_load_dwordx4 v[116:119], v[104:105], off offset:32
	global_load_dwordx4 v[120:123], v[104:105], off offset:48
	v_lshl_add_u64 v[104:105], v[104:105], 0, s[44:45]
	global_load_dwordx4 v[144:147], v[104:105], off
	global_load_dwordx4 v[148:151], v[104:105], off offset:16
	global_load_dwordx4 v[152:155], v[104:105], off offset:32
	global_load_dwordx4 v[156:159], v[104:105], off offset:48
	v_lshl_add_u64 v[104:105], v[104:105], 0, s[44:45]
	global_load_dwordx4 v[160:163], v[104:105], off
	global_load_dwordx4 v[164:167], v[104:105], off offset:16
	global_load_dwordx4 v[168:171], v[104:105], off offset:32
	global_load_dwordx4 v[172:175], v[104:105], off offset:48
	v_lshl_add_u64 v[104:105], v[104:105], 0, s[44:45]
	global_load_dwordx4 v[208:211], v[104:105], off
	global_load_dwordx4 v[212:215], v[104:105], off offset:16
	global_load_dwordx4 v[216:219], v[104:105], off offset:32
	global_load_dwordx4 v[220:223], v[104:105], off offset:48
	s_lshl_b64 s[44:45], s[24:25], 12
	v_lshl_add_u64 v[106:107], v[6:7], 0, s[44:45]
	s_mov_b64 s[44:45], 0x200000
	s_waitcnt vmcnt(12)
	v_mov_b32_e32 v224, v89
	v_mov_b32_e32 v225, v89
	v_mov_b32_e32 v226, v89
	v_mov_b32_e32 v227, v89
	v_mul_f32_e32 v108, 0x42800000, v108
	v_mul_f32_e32 v109, 0x42800000, v109
	v_mul_f32_e32 v110, 0x42800000, v110
	v_mul_f32_e32 v111, 0x42800000, v111
	v_mul_f32_e32 v112, 0x42800000, v112
	v_mul_f32_e32 v113, 0x42800000, v113
	v_mul_f32_e32 v114, 0x42800000, v114
	v_mul_f32_e32 v115, 0x42800000, v115
	v_mul_f32_e32 v116, 0x42800000, v116
	v_mul_f32_e32 v117, 0x42800000, v117
	v_mul_f32_e32 v118, 0x42800000, v118
	v_mul_f32_e32 v119, 0x42800000, v119
	v_mul_f32_e32 v120, 0x42800000, v120
	v_mul_f32_e32 v121, 0x42800000, v121
	v_mul_f32_e32 v122, 0x42800000, v122
	v_mul_f32_e32 v123, 0x42800000, v123
	v_cvt_pk_fp8_f32 v224, v108, v109
	v_cvt_pk_fp8_f32 v225, v112, v113
	v_cvt_pk_fp8_f32 v226, v116, v117
	v_cvt_pk_fp8_f32 v227, v120, v121
	v_cvt_pk_fp8_f32 v224, v110, v111 op_sel:[0,0,1]
	v_cvt_pk_fp8_f32 v225, v114, v115 op_sel:[0,0,1]
	v_cvt_pk_fp8_f32 v226, v118, v119 op_sel:[0,0,1]
	v_cvt_pk_fp8_f32 v227, v122, v123 op_sel:[0,0,1]
	global_store_dwordx4 v[106:107], v[224:227], off
	s_nop 0
	v_lshl_add_u64 v[106:107], v[106:107], 0, s[44:45]
	s_waitcnt vmcnt(9)
	v_mov_b32_e32 v228, v89
	v_mov_b32_e32 v229, v89
	v_mov_b32_e32 v230, v89
	v_mov_b32_e32 v231, v89
	v_mul_f32_e32 v144, 0x42800000, v144
	v_mul_f32_e32 v145, 0x42800000, v145
	v_mul_f32_e32 v146, 0x42800000, v146
	v_mul_f32_e32 v147, 0x42800000, v147
	v_mul_f32_e32 v148, 0x42800000, v148
	v_mul_f32_e32 v149, 0x42800000, v149
	v_mul_f32_e32 v150, 0x42800000, v150
	v_mul_f32_e32 v151, 0x42800000, v151
	v_mul_f32_e32 v152, 0x42800000, v152
	v_mul_f32_e32 v153, 0x42800000, v153
	v_mul_f32_e32 v154, 0x42800000, v154
	v_mul_f32_e32 v155, 0x42800000, v155
	v_mul_f32_e32 v156, 0x42800000, v156
	v_mul_f32_e32 v157, 0x42800000, v157
	v_mul_f32_e32 v158, 0x42800000, v158
	v_mul_f32_e32 v159, 0x42800000, v159
	v_cvt_pk_fp8_f32 v228, v144, v145
	v_cvt_pk_fp8_f32 v229, v148, v149
	v_cvt_pk_fp8_f32 v230, v152, v153
	v_cvt_pk_fp8_f32 v231, v156, v157
	v_cvt_pk_fp8_f32 v228, v146, v147 op_sel:[0,0,1]
	v_cvt_pk_fp8_f32 v229, v150, v151 op_sel:[0,0,1]
	v_cvt_pk_fp8_f32 v230, v154, v155 op_sel:[0,0,1]
	v_cvt_pk_fp8_f32 v231, v158, v159 op_sel:[0,0,1]
	global_store_dwordx4 v[106:107], v[228:231], off
	s_nop 0
	v_lshl_add_u64 v[106:107], v[106:107], 0, s[44:45]
	s_waitcnt vmcnt(6)
	v_mov_b32_e32 v232, v89
	v_mov_b32_e32 v233, v89
	v_mov_b32_e32 v234, v89
	v_mov_b32_e32 v235, v89
	v_mul_f32_e32 v160, 0x42800000, v160
	v_mul_f32_e32 v161, 0x42800000, v161
	v_mul_f32_e32 v162, 0x42800000, v162
	v_mul_f32_e32 v163, 0x42800000, v163
	v_mul_f32_e32 v164, 0x42800000, v164
	v_mul_f32_e32 v165, 0x42800000, v165
	v_mul_f32_e32 v166, 0x42800000, v166
	v_mul_f32_e32 v167, 0x42800000, v167
	v_mul_f32_e32 v168, 0x42800000, v168
	v_mul_f32_e32 v169, 0x42800000, v169
	v_mul_f32_e32 v170, 0x42800000, v170
	v_mul_f32_e32 v171, 0x42800000, v171
	v_mul_f32_e32 v172, 0x42800000, v172
	v_mul_f32_e32 v173, 0x42800000, v173
	v_mul_f32_e32 v174, 0x42800000, v174
	v_mul_f32_e32 v175, 0x42800000, v175
	v_cvt_pk_fp8_f32 v232, v160, v161
	v_cvt_pk_fp8_f32 v233, v164, v165
	v_cvt_pk_fp8_f32 v234, v168, v169
	v_cvt_pk_fp8_f32 v235, v172, v173
	v_cvt_pk_fp8_f32 v232, v162, v163 op_sel:[0,0,1]
	v_cvt_pk_fp8_f32 v233, v166, v167 op_sel:[0,0,1]
	v_cvt_pk_fp8_f32 v234, v170, v171 op_sel:[0,0,1]
	v_cvt_pk_fp8_f32 v235, v174, v175 op_sel:[0,0,1]
	global_store_dwordx4 v[106:107], v[232:235], off
	s_nop 0
	v_lshl_add_u64 v[106:107], v[106:107], 0, s[44:45]
	s_waitcnt vmcnt(3)
	v_mov_b32_e32 v236, v89
	v_mov_b32_e32 v237, v89
	v_mov_b32_e32 v238, v89
	v_mov_b32_e32 v239, v89
	v_mul_f32_e32 v208, 0x42800000, v208
	v_mul_f32_e32 v209, 0x42800000, v209
	v_mul_f32_e32 v210, 0x42800000, v210
	v_mul_f32_e32 v211, 0x42800000, v211
	v_mul_f32_e32 v212, 0x42800000, v212
	v_mul_f32_e32 v213, 0x42800000, v213
	v_mul_f32_e32 v214, 0x42800000, v214
	v_mul_f32_e32 v215, 0x42800000, v215
	v_mul_f32_e32 v216, 0x42800000, v216
	v_mul_f32_e32 v217, 0x42800000, v217
	v_mul_f32_e32 v218, 0x42800000, v218
	v_mul_f32_e32 v219, 0x42800000, v219
	v_mul_f32_e32 v220, 0x42800000, v220
	v_mul_f32_e32 v221, 0x42800000, v221
	v_mul_f32_e32 v222, 0x42800000, v222
	v_mul_f32_e32 v223, 0x42800000, v223
	v_cvt_pk_fp8_f32 v236, v208, v209
	v_cvt_pk_fp8_f32 v237, v212, v213
	v_cvt_pk_fp8_f32 v238, v216, v217
	v_cvt_pk_fp8_f32 v239, v220, v221
	v_cvt_pk_fp8_f32 v236, v210, v211 op_sel:[0,0,1]
	v_cvt_pk_fp8_f32 v237, v214, v215 op_sel:[0,0,1]
	v_cvt_pk_fp8_f32 v238, v218, v219 op_sel:[0,0,1]
	v_cvt_pk_fp8_f32 v239, v222, v223 op_sel:[0,0,1]
	global_store_dwordx4 v[106:107], v[236:239], off
	v_readlane_b32 s4, v252, 15
	s_nop 0
	s_mul_i32 s4, s4, 3
	s_add_i32 s50, s50, s4
	v_readlane_b32 s4, v252, 17
	s_nop 0
	s_mul_i32 s4, s4, 3
	s_add_i32 s49, s49, s4
	v_readlane_b32 s4, v252, 19
	s_nop 0
	s_mul_i32 s4, s4, 3
	s_add_i32 s48, s48, s4
	v_readlane_b32 s4, v252, 21
	s_nop 0
	s_mul_i32 s4, s4, 3
	s_add_i32 s47, s47, s4
	v_readlane_b32 s4, v252, 23
	s_nop 0
	s_mul_i32 s4, s4, 3
	s_add_i32 s46, s46, s4
	s_mul_i32 s4, s23, 3
	s_add_i32 s51, s51, s4
	s_mul_i32 s4, s72, 3
	s_add_i32 s1, s1, s4
	s_branch .LBB0_22
; DEVI void convert_chunk_fp8(const float* __restrict__ src, unsigned char* __restrict__ dst, float scale, int tid) {
;   int o = tid * 16;
;   uint4 r;
;   unsigned rr[4];
; #pragma unroll
;   for (int q = 0; q < 4; ++q) {
;     float4 a = *reinterpret_cast<const float4*>(src + o + q * 4);
;     int p = __builtin_amdgcn_cvt_pk_fp8_f32(a.x * scale, a.y * scale, 0, false);
;     p = __builtin_amdgcn_cvt_pk_fp8_f32(a.z * scale, a.w * scale, p, true);
;     rr[q] = (unsigned)p;
;   }
;   r = make_uint4(rr[0], rr[1], rr[2], rr[3]);
;   *reinterpret_cast<uint4*>(dst + o) = r;
; }
.Lpb_u_single:
	s_lshl_b64 s[44:45], s[24:25], 14
	v_lshl_add_u64 v[30:31], v[16:17], 0, s[44:45]
	global_load_dwordx4 v[26:29], v[30:31], off
	global_load_dwordx4 v[50:53], v[30:31], off offset:16
	global_load_dwordx4 v[54:57], v[30:31], off offset:32
	global_load_dwordx4 v[58:61], v[30:31], off offset:48
	v_mov_b32_e32 v100, v89
	v_mov_b32_e32 v101, v89
	v_mov_b32_e32 v102, v89
	v_mov_b32_e32 v103, v89
	s_lshl_b64 s[44:45], s[24:25], 12
	s_waitcnt vmcnt(3)
	v_mul_f32_e32 v25, 0x42800000, v26
	v_mul_f32_e32 v26, 0x42800000, v27
	v_mul_f32_e32 v27, 0x42800000, v28
	v_mul_f32_e32 v28, 0x42800000, v29
	s_waitcnt vmcnt(2)
	v_mul_f32_e32 v29, 0x42800000, v50
	v_mul_f32_e32 v30, 0x42800000, v51
	s_waitcnt vmcnt(1)
	v_mul_f32_e32 v50, 0x42800000, v54
	v_mul_f32_e32 v51, 0x42800000, v55
	s_waitcnt vmcnt(0)
	v_mul_f32_e32 v54, 0x42800000, v58
	v_mul_f32_e32 v55, 0x42800000, v59
	v_cvt_pk_fp8_f32 v100, v25, v26
	v_cvt_pk_fp8_f32 v101, v29, v30
	v_cvt_pk_fp8_f32 v102, v50, v51
	v_cvt_pk_fp8_f32 v103, v54, v55
	v_mul_f32_e32 v31, 0x42800000, v52
	v_mul_f32_e32 v49, 0x42800000, v53
	v_mul_f32_e32 v52, 0x42800000, v56
	v_mul_f32_e32 v53, 0x42800000, v57
	v_mul_f32_e32 v56, 0x42800000, v60
	v_mul_f32_e32 v57, 0x42800000, v61
	v_cvt_pk_fp8_f32 v100, v27, v28 op_sel:[0,0,1]
	v_cvt_pk_fp8_f32 v101, v31, v49 op_sel:[0,0,1]
	v_cvt_pk_fp8_f32 v102, v52, v53 op_sel:[0,0,1]
	v_cvt_pk_fp8_f32 v103, v56, v57 op_sel:[0,0,1]
	v_lshl_add_u64 v[26:27], v[6:7], 0, s[44:45]
	global_store_dwordx4 v[26:27], v[100:103], off
